# diff-attention main loop: loop control rotated in front of the closing barrier (back-edge rotation, guide 7.11)
# speedup vs baseline: 1.0016x; 1.0016x over previous
; #define WAIT_BAR(N) asm volatile("s_waitcnt vmcnt(" #N ") lgkmcnt(0)\n\ts_barrier":::"memory")
;   #define RESC() do{ if(resc){ asm volatile("s_waitcnt lgkmcnt(0)":::"memory"); \
;       _Pragma("unroll") for(int d_=0;d_<ND;++d_) _Pragma("unroll") for(int r=0;r<16;++r)o[d_][r]*=wsf[crow(r,hi)]; } }while(0)
;   #define ROT() do{sl_prev=sl_cur;sl_cur=sl_next;sl_next=(sl_next==(NSLOT-1)*SLOTB)?0:sl_next+SLOTB;}while(0)
; template<int MODE,int THRL> __device__ __forceinline__ void attn_unit(const bf16*Qw0,int PQ,const bf16*__restrict__ Kh,int PK,const bf16*__restrict__ Vh,int PV,bf16*Ow0,int PO,int NT,int nabase,int nar0,const float*rpbh,char*shm,int&rot,bool pre,bool hasn,long dKn,long dVn){
;     ...
;   int t=1;
;   for(;t+5<NT;t+=2){
;     STEP(pB0,pB1,pA0,pA1,t,true,true,true);     if(MODE==2){WAIT_BAR(3);}else{WAIT_BAR(2);} RESC(); ROT();
;     STEP(pA0,pA1,pB0,pB1,t+1,true,true,true);   if(MODE==2){WAIT_BAR(3);}else{WAIT_BAR(2);} RESC(); ROT();
.LBB0_1130:
	v_add_u32_e32 v1, s4, v248
	ds_read_b128 v[206:209], v1
	ds_read_b128 v[198:201], v1 offset:512
	s_waitcnt lgkmcnt(14)
	v_mfma_f32_32x32x16_bf16 v[34:49], v[154:157], v[138:141], v[34:49]
	v_exp_f32_e32 v98, v98
	v_exp_f32_e32 v99, v99
	v_exp_f32_e32 v100, v100
	ds_read_b64_tr_b16 v[138:139], v226 offset:37888
	ds_read_b64_tr_b16 v[140:141], v226 offset:38400
	ds_read_b128 v[202:205], v1 offset:2048
	ds_read_b128 v[194:197], v1 offset:2560
	v_mfma_f32_32x32x16_bf16 v[50:65], v[150:153], v[134:137], v[50:65]
	v_exp_f32_e32 v101, v101
	v_exp_f32_e32 v102, v102
	v_exp_f32_e32 v103, v103
	ds_read_b64_tr_b16 v[134:135], v226 offset:34816
	ds_read_b64_tr_b16 v[136:137], v226 offset:35328
	ds_read_b128 v[190:193], v1 offset:4096
	ds_read_b128 v[186:189], v1 offset:4608
	s_waitcnt lgkmcnt(14)
	v_mfma_f32_32x32x16_bf16 v[34:49], v[150:153], v[130:133], v[34:49]
	v_exp_f32_e32 v104, v104
	v_exp_f32_e32 v105, v105
	v_exp_f32_e32 v106, v106
	ds_read_b64_tr_b16 v[130:131], v226 offset:38912
	ds_read_b64_tr_b16 v[132:133], v226 offset:39424
	ds_read_b128 v[182:185], v1 offset:6144
	ds_read_b128 v[178:181], v1 offset:6656
	v_mfma_f32_32x32x16_bf16 v[50:65], v[146:149], v[114:117], v[50:65]
	v_exp_f32_e32 v107, v107
	v_exp_f32_e32 v108, v108
	v_exp_f32_e32 v109, v109
	ds_read_b64_tr_b16 v[114:115], v226 offset:35840
	ds_read_b64_tr_b16 v[116:117], v226 offset:36352
	v_mfma_f32_32x32x16_bf16 v[34:49], v[146:149], v[118:121], v[34:49]
	v_exp_f32_e32 v110, v110
	v_exp_f32_e32 v111, v111
	v_exp_f32_e32 v112, v112
	ds_read_b64_tr_b16 v[118:119], v226 offset:39936
	ds_read_b64_tr_b16 v[120:121], v226 offset:40448
	v_mfma_f32_32x32x16_bf16 v[18:33], v[158:161], v[142:145], v[18:33]
	v_exp_f32_e32 v113, v113
	v_exp_f32_e32 v82, v82
	v_exp_f32_e32 v83, v83
	s_waitcnt lgkmcnt(14)
	v_mfma_f32_32x32x16_bf16 v[2:17], v[158:161], v[126:129], v[2:17]
	v_exp_f32_e32 v84, v84
	v_exp_f32_e32 v85, v85
	v_mfma_f32_32x32x16_bf16 v[18:33], v[154:157], v[122:125], v[18:33]
	v_exp_f32_e32 v86, v86
	v_exp_f32_e32 v87, v87
	v_mfma_f32_32x32x16_bf16 v[2:17], v[154:157], v[138:141], v[2:17]
	v_exp_f32_e32 v88, v88
	v_exp_f32_e32 v89, v89
	s_waitcnt lgkmcnt(10)
	v_mfma_f32_32x32x16_bf16 v[18:33], v[150:153], v[134:137], v[18:33]
	v_exp_f32_e32 v90, v90
	v_exp_f32_e32 v91, v91
	s_waitcnt lgkmcnt(6)
	v_mfma_f32_32x32x16_bf16 v[2:17], v[150:153], v[130:133], v[2:17]
	v_exp_f32_e32 v92, v92
	v_exp_f32_e32 v93, v93
	s_waitcnt lgkmcnt(2)
	v_mfma_f32_32x32x16_bf16 v[18:33], v[146:149], v[114:117], v[18:33]
	v_exp_f32_e32 v94, v94
	v_exp_f32_e32 v95, v95
	s_waitcnt lgkmcnt(0)
	v_mfma_f32_32x32x16_bf16 v[2:17], v[146:149], v[118:121], v[2:17]
	v_exp_f32_e32 v96, v96
	v_exp_f32_e32 v97, v97
	s_add_i32 s8, s4, 0x2000
	s_cmpk_lg_i32 s4, 0x4000
	s_cselect_b32 s8, s8, 0
	s_add_i32 s90, s90, 2
	s_cmpk_lt_u32 s90, 0x7d
	v_lshl_add_u64 v[212:213], v[212:213], 0, s[60:61]
	s_cselect_b32 s98, 1, 0
	s_cbranch_scc0 .Lrot_m2_noadv
	v_mov_b64_e32 v[214:215], v[216:217]
	s_mov_b32 s9, s84
	s_mov_b32 s15, s4
	s_mov_b32 s84, s8
.Lrot_m2_noadv:
	s_waitcnt vmcnt(3) lgkmcnt(0)
	s_barrier
	s_andn2_b64 vcc, exec, s[86:87]
	s_cbranch_vccnz .LBB0_1132
	s_waitcnt lgkmcnt(0)
	v_add_u32_e32 v1, s3, v245
	ds_read_b128 v[114:117], v1 offset:96
	ds_read_b128 v[118:121], v1 offset:64
	ds_read_b128 v[122:125], v1 offset:32
	ds_read_b128 v[126:129], v1
	s_waitcnt lgkmcnt(3)
	v_mul_f32_e32 v62, v62, v114
	v_mul_f32_e32 v63, v63, v115
	s_waitcnt lgkmcnt(2)
	v_mul_f32_e32 v58, v58, v118
	v_mul_f32_e32 v59, v59, v119
	s_waitcnt lgkmcnt(1)
	v_mul_f32_e32 v54, v54, v122
	v_mul_f32_e32 v55, v55, v123
	v_mul_f32_e32 v64, v64, v116
	v_mul_f32_e32 v65, v65, v117
	v_mul_f32_e32 v60, v60, v120
	v_mul_f32_e32 v61, v61, v121
	v_mul_f32_e32 v56, v56, v124
	v_mul_f32_e32 v57, v57, v125
	s_waitcnt lgkmcnt(0)
	v_mul_f32_e32 v52, v52, v128
	v_mul_f32_e32 v53, v53, v129
	v_mul_f32_e32 v50, v50, v126
	v_mul_f32_e32 v51, v51, v127
	v_mul_f32_e32 v46, v46, v114
	v_mul_f32_e32 v47, v47, v115
	v_mul_f32_e32 v42, v42, v118
	v_mul_f32_e32 v43, v43, v119
	v_mul_f32_e32 v38, v38, v122
	v_mul_f32_e32 v39, v39, v123
	v_mul_f32_e32 v48, v48, v116
	v_mul_f32_e32 v49, v49, v117
	v_mul_f32_e32 v44, v44, v120
	v_mul_f32_e32 v45, v45, v121
	v_mul_f32_e32 v40, v40, v124
	v_mul_f32_e32 v41, v41, v125
	v_mul_f32_e32 v36, v36, v128
	v_mul_f32_e32 v37, v37, v129
	v_mul_f32_e32 v34, v34, v126
	v_mul_f32_e32 v35, v35, v127
	v_mul_f32_e32 v30, v30, v114
	v_mul_f32_e32 v31, v31, v115
	v_mul_f32_e32 v26, v26, v118
	v_mul_f32_e32 v27, v27, v119
	v_mul_f32_e32 v22, v22, v122
	v_mul_f32_e32 v23, v23, v123
	v_mul_f32_e32 v32, v32, v116
	v_mul_f32_e32 v33, v33, v117
	v_mul_f32_e32 v28, v28, v120
	v_mul_f32_e32 v29, v29, v121
	v_mul_f32_e32 v24, v24, v124
	v_mul_f32_e32 v25, v25, v125
	v_mul_f32_e32 v20, v20, v128
	v_mul_f32_e32 v21, v21, v129
	v_mul_f32_e32 v18, v18, v126
	v_mul_f32_e32 v19, v19, v127
	v_mul_f32_e32 v14, v14, v114
	v_mul_f32_e32 v15, v15, v115
	v_mul_f32_e32 v10, v10, v118
	v_mul_f32_e32 v11, v11, v119
	v_mul_f32_e32 v6, v6, v122
	v_mul_f32_e32 v7, v7, v123
	v_mul_f32_e32 v16, v16, v116
	v_mul_f32_e32 v17, v17, v117
	v_mul_f32_e32 v12, v12, v120
	v_mul_f32_e32 v13, v13, v121
	v_mul_f32_e32 v8, v8, v124
	v_mul_f32_e32 v9, v9, v125
	v_mul_f32_e32 v4, v4, v128
	v_mul_f32_e32 v5, v5, v129
	v_mul_f32_e32 v2, v2, v126
	v_mul_f32_e32 v3, v3, v127
.LBB0_1132:
	s_cmp_lg_u32 s98, 0
	s_cbranch_scc1 .LBB0_1126
	s_branch .LBB0_1140
